# EpiRes epilogues (out-proj, FFN-down): gate loaded once, x loads batched 8 deep, stores issued behind next loads
# speedup vs baseline: 1.0535x; 1.0032x over previous
.LBB0_1610:
	v_or_b32_e32 v128, s20, v140
	v_lshl_add_u32 v130, v137, 6, v128
	v_lshlrev_b32_e32 v128, 5, v138
	v_lshlrev_b32_e32 v129, 2, v139
	v_or3_b32 v128, v128, v129, s18
	v_lshlrev_b32_e32 v129, 2, v128
	v_ashrrev_i32_e32 v131, 11, v130
	v_mul_u32_u24_e32 v132, 0x6000, v131
	v_add_u32_e32 v132, v132, v129
	global_load_dwordx4 v[144:147], v132, s[14:15]
	global_load_dwordx4 v[148:151], v132, s[14:15] offset:64
	global_load_dwordx4 v[152:155], v132, s[14:15] offset:512
	global_load_dwordx4 v[156:159], v132, s[14:15] offset:576
	s_cmp_eq_u32 s29, s28
	s_cselect_b64 s[8:9], -1, 0
	v_mov_b32_e32 v225, v196
	v_lshl_add_u32 v137, v130, 12, v129
	v_or_b32_e32 v133, 16, v130
	v_lshl_add_u32 v138, v133, 12, v129
	v_or_b32_e32 v133, 32, v130
	v_lshl_add_u32 v139, v133, 12, v129
	v_or_b32_e32 v133, 48, v130
	v_lshl_add_u32 v140, v133, 12, v129
	global_load_dwordx4 v[160:163], v137, s[12:13]
	global_load_dwordx4 v[164:167], v137, s[12:13] offset:64
	global_load_dwordx4 v[168:171], v138, s[12:13]
	global_load_dwordx4 v[172:175], v138, s[12:13] offset:64
	global_load_dwordx4 v[176:179], v139, s[12:13]
	global_load_dwordx4 v[180:183], v139, s[12:13] offset:64
	global_load_dwordx4 v[184:187], v140, s[12:13]
	global_load_dwordx4 v[188:191], v140, s[12:13] offset:64
	v_or_b32_e32 v133, 0x80, v130
	v_lshl_add_u32 v141, v133, 12, v129
	v_or_b32_e32 v133, 0x90, v130
	v_lshl_add_u32 v142, v133, 12, v129
	v_or_b32_e32 v133, 0xa0, v130
	v_lshl_add_u32 v143, v133, 12, v129
	v_or_b32_e32 v133, 0xb0, v130
	v_lshl_add_u32 v131, v133, 12, v129
	s_waitcnt vmcnt(0)
	v_pk_fma_f32 v[126:127], v[126:127], v[146:147], v[162:163]
	v_pk_fma_f32 v[124:125], v[124:125], v[144:145], v[160:161]
	v_pk_fma_f32 v[122:123], v[122:123], v[150:151], v[166:167]
	v_pk_fma_f32 v[120:121], v[120:121], v[148:149], v[164:165]
	v_pk_fma_f32 v[118:119], v[118:119], v[146:147], v[170:171]
	v_pk_fma_f32 v[116:117], v[116:117], v[144:145], v[168:169]
	v_pk_fma_f32 v[114:115], v[114:115], v[150:151], v[174:175]
	v_pk_fma_f32 v[112:113], v[112:113], v[148:149], v[172:173]
	v_pk_fma_f32 v[110:111], v[110:111], v[146:147], v[178:179]
	v_pk_fma_f32 v[108:109], v[108:109], v[144:145], v[176:177]
	v_pk_fma_f32 v[106:107], v[106:107], v[150:151], v[182:183]
	v_pk_fma_f32 v[104:105], v[104:105], v[148:149], v[180:181]
	v_pk_fma_f32 v[102:103], v[102:103], v[146:147], v[186:187]
	v_pk_fma_f32 v[100:101], v[100:101], v[144:145], v[184:185]
	v_pk_fma_f32 v[98:99], v[98:99], v[150:151], v[190:191]
	v_pk_fma_f32 v[96:97], v[96:97], v[148:149], v[188:189]
	global_load_dwordx4 v[160:163], v137, s[12:13] offset:512
	global_load_dwordx4 v[164:167], v137, s[12:13] offset:576
	global_load_dwordx4 v[168:171], v138, s[12:13] offset:512
	global_load_dwordx4 v[172:175], v138, s[12:13] offset:576
	global_load_dwordx4 v[176:179], v139, s[12:13] offset:512
	global_load_dwordx4 v[180:183], v139, s[12:13] offset:576
	global_load_dwordx4 v[184:187], v140, s[12:13] offset:512
	global_load_dwordx4 v[188:191], v140, s[12:13] offset:576
	global_store_dwordx4 v137, v[124:127], s[4:5]
	global_store_dwordx4 v137, v[120:123], s[4:5] offset:64
	global_store_dwordx4 v138, v[116:119], s[4:5]
	global_store_dwordx4 v138, v[112:115], s[4:5] offset:64
	global_store_dwordx4 v139, v[108:111], s[4:5]
	global_store_dwordx4 v139, v[104:107], s[4:5] offset:64
	global_store_dwordx4 v140, v[100:103], s[4:5]
	global_store_dwordx4 v140, v[96:99], s[4:5] offset:64
	s_waitcnt vmcnt(8)
	v_pk_fma_f32 v[94:95], v[94:95], v[154:155], v[162:163]
	v_pk_fma_f32 v[92:93], v[92:93], v[152:153], v[160:161]
	v_pk_fma_f32 v[90:91], v[90:91], v[158:159], v[166:167]
	v_pk_fma_f32 v[88:89], v[88:89], v[156:157], v[164:165]
	v_pk_fma_f32 v[86:87], v[86:87], v[154:155], v[170:171]
	v_pk_fma_f32 v[84:85], v[84:85], v[152:153], v[168:169]
	v_pk_fma_f32 v[82:83], v[82:83], v[158:159], v[174:175]
	v_pk_fma_f32 v[80:81], v[80:81], v[156:157], v[172:173]
	v_pk_fma_f32 v[78:79], v[78:79], v[154:155], v[178:179]
	v_pk_fma_f32 v[76:77], v[76:77], v[152:153], v[176:177]
	v_pk_fma_f32 v[74:75], v[74:75], v[158:159], v[182:183]
	v_pk_fma_f32 v[72:73], v[72:73], v[156:157], v[180:181]
	v_pk_fma_f32 v[70:71], v[70:71], v[154:155], v[186:187]
	v_pk_fma_f32 v[68:69], v[68:69], v[152:153], v[184:185]
	v_pk_fma_f32 v[62:63], v[62:63], v[158:159], v[190:191]
	v_pk_fma_f32 v[60:61], v[60:61], v[156:157], v[188:189]
	global_load_dwordx4 v[160:163], v141, s[12:13]
	global_load_dwordx4 v[164:167], v141, s[12:13] offset:64
	global_load_dwordx4 v[168:171], v142, s[12:13]
	global_load_dwordx4 v[172:175], v142, s[12:13] offset:64
	global_load_dwordx4 v[176:179], v143, s[12:13]
	global_load_dwordx4 v[180:183], v143, s[12:13] offset:64
	global_load_dwordx4 v[184:187], v131, s[12:13]
	global_load_dwordx4 v[188:191], v131, s[12:13] offset:64
	global_store_dwordx4 v137, v[92:95], s[4:5] offset:512
	global_store_dwordx4 v137, v[88:91], s[4:5] offset:576
	global_store_dwordx4 v138, v[84:87], s[4:5] offset:512
	global_store_dwordx4 v138, v[80:83], s[4:5] offset:576
	global_store_dwordx4 v139, v[76:79], s[4:5] offset:512
	global_store_dwordx4 v139, v[72:75], s[4:5] offset:576
	global_store_dwordx4 v140, v[68:71], s[4:5] offset:512
	global_store_dwordx4 v140, v[60:63], s[4:5] offset:576
	s_waitcnt vmcnt(8)
	v_pk_fma_f32 v[66:67], v[66:67], v[146:147], v[162:163]
	v_pk_fma_f32 v[64:65], v[64:65], v[144:145], v[160:161]
	v_pk_fma_f32 v[58:59], v[58:59], v[150:151], v[166:167]
	v_pk_fma_f32 v[56:57], v[56:57], v[148:149], v[164:165]
	v_pk_fma_f32 v[54:55], v[54:55], v[146:147], v[170:171]
	v_pk_fma_f32 v[52:53], v[52:53], v[144:145], v[168:169]
	v_pk_fma_f32 v[50:51], v[50:51], v[150:151], v[174:175]
	v_pk_fma_f32 v[48:49], v[48:49], v[148:149], v[172:173]
	v_pk_fma_f32 v[46:47], v[46:47], v[146:147], v[178:179]
	v_pk_fma_f32 v[44:45], v[44:45], v[144:145], v[176:177]
	v_pk_fma_f32 v[42:43], v[42:43], v[150:151], v[182:183]
	v_pk_fma_f32 v[40:41], v[40:41], v[148:149], v[180:181]
	v_pk_fma_f32 v[38:39], v[38:39], v[146:147], v[186:187]
	v_pk_fma_f32 v[36:37], v[36:37], v[144:145], v[184:185]
	v_pk_fma_f32 v[34:35], v[34:35], v[150:151], v[190:191]
	v_pk_fma_f32 v[32:33], v[32:33], v[148:149], v[188:189]
	global_load_dwordx4 v[160:163], v141, s[12:13] offset:512
	global_load_dwordx4 v[164:167], v141, s[12:13] offset:576
	global_load_dwordx4 v[168:171], v142, s[12:13] offset:512
	global_load_dwordx4 v[172:175], v142, s[12:13] offset:576
	global_load_dwordx4 v[176:179], v143, s[12:13] offset:512
	global_load_dwordx4 v[180:183], v143, s[12:13] offset:576
	global_load_dwordx4 v[184:187], v131, s[12:13] offset:512
	global_load_dwordx4 v[188:191], v131, s[12:13] offset:576
	global_store_dwordx4 v141, v[64:67], s[4:5]
	global_store_dwordx4 v141, v[56:59], s[4:5] offset:64
	global_store_dwordx4 v142, v[52:55], s[4:5]
	global_store_dwordx4 v142, v[48:51], s[4:5] offset:64
	global_store_dwordx4 v143, v[44:47], s[4:5]
	global_store_dwordx4 v143, v[40:43], s[4:5] offset:64
	global_store_dwordx4 v131, v[36:39], s[4:5]
	global_store_dwordx4 v131, v[32:35], s[4:5] offset:64
	s_waitcnt vmcnt(8)
	v_pk_fma_f32 v[30:31], v[30:31], v[154:155], v[162:163]
	v_pk_fma_f32 v[28:29], v[28:29], v[152:153], v[160:161]
	v_pk_fma_f32 v[26:27], v[26:27], v[158:159], v[166:167]
	v_pk_fma_f32 v[24:25], v[24:25], v[156:157], v[164:165]
	v_pk_fma_f32 v[22:23], v[22:23], v[154:155], v[170:171]
	v_pk_fma_f32 v[20:21], v[20:21], v[152:153], v[168:169]
	v_pk_fma_f32 v[18:19], v[18:19], v[158:159], v[174:175]
	v_pk_fma_f32 v[16:17], v[16:17], v[156:157], v[172:173]
	v_pk_fma_f32 v[14:15], v[14:15], v[154:155], v[178:179]
	v_pk_fma_f32 v[12:13], v[12:13], v[152:153], v[176:177]
	v_pk_fma_f32 v[10:11], v[10:11], v[158:159], v[182:183]
	v_pk_fma_f32 v[8:9], v[8:9], v[156:157], v[180:181]
	v_pk_fma_f32 v[6:7], v[6:7], v[154:155], v[186:187]
	v_pk_fma_f32 v[4:5], v[4:5], v[152:153], v[184:185]
	v_pk_fma_f32 v[2:3], v[2:3], v[158:159], v[190:191]
	v_pk_fma_f32 v[0:1], v[0:1], v[156:157], v[188:189]
	global_store_dwordx4 v141, v[28:31], s[4:5] offset:512
	global_store_dwordx4 v141, v[24:27], s[4:5] offset:576
	global_store_dwordx4 v142, v[20:23], s[4:5] offset:512
	global_store_dwordx4 v142, v[16:19], s[4:5] offset:576
	global_store_dwordx4 v143, v[12:15], s[4:5] offset:512
	global_store_dwordx4 v143, v[8:11], s[4:5] offset:576
	global_store_dwordx4 v131, v[4:7], s[4:5] offset:512
	global_store_dwordx4 v131, v[0:3], s[4:5] offset:576
	s_waitcnt lgkmcnt(0)
	s_barrier

.LBB0_1837:
	v_or_b32_e32 v128, s26, v140
	s_lshl_b32 s12, s23, 8
	v_lshl_add_u32 v130, v137, 6, v128
	v_lshlrev_b32_e32 v128, 5, v138
	v_lshlrev_b32_e32 v129, 2, v139
	v_or3_b32 v128, v128, v129, s12
	v_lshlrev_b32_e32 v129, 2, v128
	v_ashrrev_i32_e32 v131, 11, v130
	v_mul_u32_u24_e32 v132, 0x6000, v131
	v_add_u32_e32 v132, v132, v129
	global_load_dwordx4 v[144:147], v132, s[4:5]
	global_load_dwordx4 v[148:151], v132, s[4:5] offset:64
	global_load_dwordx4 v[152:155], v132, s[4:5] offset:512
	global_load_dwordx4 v[156:159], v132, s[4:5] offset:576
	s_cmp_eq_u32 s21, s20
	s_cselect_b64 s[12:13], -1, 0
	v_mov_b32_e32 v225, v196
	v_lshl_add_u32 v137, v130, 12, v129
	v_or_b32_e32 v133, 16, v130
	v_lshl_add_u32 v138, v133, 12, v129
	v_or_b32_e32 v133, 32, v130
	v_lshl_add_u32 v139, v133, 12, v129
	v_or_b32_e32 v133, 48, v130
	v_lshl_add_u32 v140, v133, 12, v129
	global_load_dwordx4 v[160:163], v137, s[0:1]
	global_load_dwordx4 v[164:167], v137, s[0:1] offset:64
	global_load_dwordx4 v[168:171], v138, s[0:1]
	global_load_dwordx4 v[172:175], v138, s[0:1] offset:64
	global_load_dwordx4 v[176:179], v139, s[0:1]
	global_load_dwordx4 v[180:183], v139, s[0:1] offset:64
	global_load_dwordx4 v[184:187], v140, s[0:1]
	global_load_dwordx4 v[188:191], v140, s[0:1] offset:64
	v_or_b32_e32 v133, 0x80, v130
	v_lshl_add_u32 v141, v133, 12, v129
	v_or_b32_e32 v133, 0x90, v130
	v_lshl_add_u32 v142, v133, 12, v129
	v_or_b32_e32 v133, 0xa0, v130
	v_lshl_add_u32 v143, v133, 12, v129
	v_or_b32_e32 v133, 0xb0, v130
	v_lshl_add_u32 v131, v133, 12, v129
	s_waitcnt vmcnt(0)
	v_pk_fma_f32 v[126:127], v[126:127], v[146:147], v[162:163]
	v_pk_fma_f32 v[124:125], v[124:125], v[144:145], v[160:161]
	v_pk_fma_f32 v[122:123], v[122:123], v[150:151], v[166:167]
	v_pk_fma_f32 v[120:121], v[120:121], v[148:149], v[164:165]
	v_pk_fma_f32 v[118:119], v[118:119], v[146:147], v[170:171]
	v_pk_fma_f32 v[116:117], v[116:117], v[144:145], v[168:169]
	v_pk_fma_f32 v[114:115], v[114:115], v[150:151], v[174:175]
	v_pk_fma_f32 v[112:113], v[112:113], v[148:149], v[172:173]
	v_pk_fma_f32 v[110:111], v[110:111], v[146:147], v[178:179]
	v_pk_fma_f32 v[108:109], v[108:109], v[144:145], v[176:177]
	v_pk_fma_f32 v[106:107], v[106:107], v[150:151], v[182:183]
	v_pk_fma_f32 v[104:105], v[104:105], v[148:149], v[180:181]
	v_pk_fma_f32 v[102:103], v[102:103], v[146:147], v[186:187]
	v_pk_fma_f32 v[100:101], v[100:101], v[144:145], v[184:185]
	v_pk_fma_f32 v[98:99], v[98:99], v[150:151], v[190:191]
	v_pk_fma_f32 v[96:97], v[96:97], v[148:149], v[188:189]
	global_load_dwordx4 v[160:163], v137, s[0:1] offset:512
	global_load_dwordx4 v[164:167], v137, s[0:1] offset:576
	global_load_dwordx4 v[168:171], v138, s[0:1] offset:512
	global_load_dwordx4 v[172:175], v138, s[0:1] offset:576
	global_load_dwordx4 v[176:179], v139, s[0:1] offset:512
	global_load_dwordx4 v[180:183], v139, s[0:1] offset:576
	global_load_dwordx4 v[184:187], v140, s[0:1] offset:512
	global_load_dwordx4 v[188:191], v140, s[0:1] offset:576
	global_store_dwordx4 v137, v[124:127], s[0:1]
	global_store_dwordx4 v137, v[120:123], s[0:1] offset:64
	global_store_dwordx4 v138, v[116:119], s[0:1]
	global_store_dwordx4 v138, v[112:115], s[0:1] offset:64
	global_store_dwordx4 v139, v[108:111], s[0:1]
	global_store_dwordx4 v139, v[104:107], s[0:1] offset:64
	global_store_dwordx4 v140, v[100:103], s[0:1]
	global_store_dwordx4 v140, v[96:99], s[0:1] offset:64
	s_waitcnt vmcnt(8)
	v_pk_fma_f32 v[94:95], v[94:95], v[154:155], v[162:163]
	v_pk_fma_f32 v[92:93], v[92:93], v[152:153], v[160:161]
	v_pk_fma_f32 v[90:91], v[90:91], v[158:159], v[166:167]
	v_pk_fma_f32 v[88:89], v[88:89], v[156:157], v[164:165]
	v_pk_fma_f32 v[86:87], v[86:87], v[154:155], v[170:171]
	v_pk_fma_f32 v[84:85], v[84:85], v[152:153], v[168:169]
	v_pk_fma_f32 v[82:83], v[82:83], v[158:159], v[174:175]
	v_pk_fma_f32 v[80:81], v[80:81], v[156:157], v[172:173]
	v_pk_fma_f32 v[78:79], v[78:79], v[154:155], v[178:179]
	v_pk_fma_f32 v[76:77], v[76:77], v[152:153], v[176:177]
	v_pk_fma_f32 v[74:75], v[74:75], v[158:159], v[182:183]
	v_pk_fma_f32 v[72:73], v[72:73], v[156:157], v[180:181]
	v_pk_fma_f32 v[70:71], v[70:71], v[154:155], v[186:187]
	v_pk_fma_f32 v[68:69], v[68:69], v[152:153], v[184:185]
	v_pk_fma_f32 v[66:67], v[66:67], v[158:159], v[190:191]
	v_pk_fma_f32 v[64:65], v[64:65], v[156:157], v[188:189]
	global_load_dwordx4 v[160:163], v141, s[0:1]
	global_load_dwordx4 v[164:167], v141, s[0:1] offset:64
	global_load_dwordx4 v[168:171], v142, s[0:1]
	global_load_dwordx4 v[172:175], v142, s[0:1] offset:64
	global_load_dwordx4 v[176:179], v143, s[0:1]
	global_load_dwordx4 v[180:183], v143, s[0:1] offset:64
	global_load_dwordx4 v[184:187], v131, s[0:1]
	global_load_dwordx4 v[188:191], v131, s[0:1] offset:64
	global_store_dwordx4 v137, v[92:95], s[0:1] offset:512
	global_store_dwordx4 v137, v[88:91], s[0:1] offset:576
	global_store_dwordx4 v138, v[84:87], s[0:1] offset:512
	global_store_dwordx4 v138, v[80:83], s[0:1] offset:576
	global_store_dwordx4 v139, v[76:79], s[0:1] offset:512
	global_store_dwordx4 v139, v[72:75], s[0:1] offset:576
	global_store_dwordx4 v140, v[68:71], s[0:1] offset:512
	global_store_dwordx4 v140, v[64:67], s[0:1] offset:576
	s_waitcnt vmcnt(8)
	v_pk_fma_f32 v[62:63], v[62:63], v[146:147], v[162:163]
	v_pk_fma_f32 v[60:61], v[60:61], v[144:145], v[160:161]
	v_pk_fma_f32 v[58:59], v[58:59], v[150:151], v[166:167]
	v_pk_fma_f32 v[56:57], v[56:57], v[148:149], v[164:165]
	v_pk_fma_f32 v[54:55], v[54:55], v[146:147], v[170:171]
	v_pk_fma_f32 v[52:53], v[52:53], v[144:145], v[168:169]
	v_pk_fma_f32 v[50:51], v[50:51], v[150:151], v[174:175]
	v_pk_fma_f32 v[48:49], v[48:49], v[148:149], v[172:173]
	v_pk_fma_f32 v[46:47], v[46:47], v[146:147], v[178:179]
	v_pk_fma_f32 v[44:45], v[44:45], v[144:145], v[176:177]
	v_pk_fma_f32 v[42:43], v[42:43], v[150:151], v[182:183]
	v_pk_fma_f32 v[40:41], v[40:41], v[148:149], v[180:181]
	v_pk_fma_f32 v[38:39], v[38:39], v[146:147], v[186:187]
	v_pk_fma_f32 v[36:37], v[36:37], v[144:145], v[184:185]
	v_pk_fma_f32 v[34:35], v[34:35], v[150:151], v[190:191]
	v_pk_fma_f32 v[32:33], v[32:33], v[148:149], v[188:189]
	global_load_dwordx4 v[160:163], v141, s[0:1] offset:512
	global_load_dwordx4 v[164:167], v141, s[0:1] offset:576
	global_load_dwordx4 v[168:171], v142, s[0:1] offset:512
	global_load_dwordx4 v[172:175], v142, s[0:1] offset:576
	global_load_dwordx4 v[176:179], v143, s[0:1] offset:512
	global_load_dwordx4 v[180:183], v143, s[0:1] offset:576
	global_load_dwordx4 v[184:187], v131, s[0:1] offset:512
	global_load_dwordx4 v[188:191], v131, s[0:1] offset:576
	global_store_dwordx4 v141, v[60:63], s[0:1]
	global_store_dwordx4 v141, v[56:59], s[0:1] offset:64
	global_store_dwordx4 v142, v[52:55], s[0:1]
	global_store_dwordx4 v142, v[48:51], s[0:1] offset:64
	global_store_dwordx4 v143, v[44:47], s[0:1]
	global_store_dwordx4 v143, v[40:43], s[0:1] offset:64
	global_store_dwordx4 v131, v[36:39], s[0:1]
	global_store_dwordx4 v131, v[32:35], s[0:1] offset:64
	s_waitcnt vmcnt(8)
	v_pk_fma_f32 v[30:31], v[30:31], v[154:155], v[162:163]
	v_pk_fma_f32 v[28:29], v[28:29], v[152:153], v[160:161]
	v_pk_fma_f32 v[26:27], v[26:27], v[158:159], v[166:167]
	v_pk_fma_f32 v[24:25], v[24:25], v[156:157], v[164:165]
	v_pk_fma_f32 v[22:23], v[22:23], v[154:155], v[170:171]
	v_pk_fma_f32 v[20:21], v[20:21], v[152:153], v[168:169]
	v_pk_fma_f32 v[18:19], v[18:19], v[158:159], v[174:175]
	v_pk_fma_f32 v[16:17], v[16:17], v[156:157], v[172:173]
	v_pk_fma_f32 v[14:15], v[14:15], v[154:155], v[178:179]
	v_pk_fma_f32 v[12:13], v[12:13], v[152:153], v[176:177]
	v_pk_fma_f32 v[10:11], v[10:11], v[158:159], v[182:183]
	v_pk_fma_f32 v[8:9], v[8:9], v[156:157], v[180:181]
	v_pk_fma_f32 v[6:7], v[6:7], v[154:155], v[186:187]
	v_pk_fma_f32 v[4:5], v[4:5], v[152:153], v[184:185]
	v_pk_fma_f32 v[2:3], v[2:3], v[158:159], v[190:191]
	v_pk_fma_f32 v[0:1], v[0:1], v[156:157], v[188:189]
	global_store_dwordx4 v141, v[28:31], s[0:1] offset:512
	global_store_dwordx4 v141, v[24:27], s[0:1] offset:576
	global_store_dwordx4 v142, v[20:23], s[0:1] offset:512
	global_store_dwordx4 v142, v[16:19], s[0:1] offset:576
	global_store_dwordx4 v143, v[12:15], s[0:1] offset:512
	global_store_dwordx4 v143, v[8:11], s[0:1] offset:576
	global_store_dwordx4 v131, v[4:7], s[0:1] offset:512
	global_store_dwordx4 v131, v[0:3], s[0:1] offset:576
	s_waitcnt lgkmcnt(0)
	s_barrier
